# grid barrier: non-leader blocks wait on the top-level generation word directly (one fewer serial round trip per barrier)
# speedup vs baseline: 1.0042x; 1.0042x over previous
.LBB0_1014:
	s_or_b64 exec, exec, s[2:3]
	v_cvt_f32_u32_e32 v4, v2
	s_waitcnt vmcnt(0)
	v_readfirstlane_b32 s2, v3
	v_sub_u32_e32 v3, 0, v2
	v_rcp_iflag_f32_e32 v4, v4
	v_add_u32_e32 v5, s2, v1
	v_mul_f32_e32 v4, 0x4f7ffffe, v4
	v_cvt_u32_f32_e32 v4, v4
	v_mul_lo_u32 v1, v3, v4
	v_mul_hi_u32 v1, v4, v1
	v_add_u32_e32 v1, v4, v1
	v_mul_hi_u32 v1, v5, v1
	v_mul_lo_u32 v3, v1, v2
	v_sub_u32_e32 v3, v5, v3
	v_add_u32_e32 v4, 1, v1
	v_cmp_ge_u32_e32 vcc, v3, v2
	s_nop 1
	v_cndmask_b32_e32 v1, v1, v4, vcc
	v_sub_u32_e32 v4, v3, v2
	v_cndmask_b32_e32 v3, v3, v4, vcc
	v_add_u32_e32 v4, 1, v1
	v_cmp_ge_u32_e32 vcc, v3, v2
	v_add_u32_e32 v3, 1, v5
	s_nop 0
	v_cndmask_b32_e32 v1, v1, v4, vcc
	v_mul_lo_u32 v4, v2, v1
	v_add_u32_e32 v2, v4, v2
	v_cmp_ne_u32_e32 vcc, v3, v2
	s_and_saveexec_b64 s[2:3], vcc
	s_xor_b64 s[2:3], exec, s[2:3]
	s_cbranch_execz .LBB0_1028
	v_readlane_b32 s6, v254, 36
	v_readlane_b32 s7, v254, 37
	s_waitcnt lgkmcnt(0)
	s_nop 3
	global_load_dword v0, v177, s[6:7] sc1
	s_waitcnt vmcnt(0)
	v_cmp_eq_u32_e32 vcc, v0, v1
	s_and_saveexec_b64 s[6:7], vcc
	s_cbranch_execz .LBB0_1027
	s_mov_b32 s20, 1
	s_mov_b64 s[8:9], 0
	s_branch .LBB0_1018

.LBB0_1022:
	v_readlane_b32 s12, v254, 36
	v_readlane_b32 s13, v254, 37
	s_add_i32 s20, s20, 1
	s_mov_b64 s[14:15], -1
	s_nop 2
	global_load_dword v0, v177, s[12:13] sc1
	s_waitcnt vmcnt(0)
	v_cmp_ne_u32_e32 vcc, v0, v1
	s_orn2_b64 s[12:13], vcc, exec
	s_branch .LBB0_1017
